# v105: v99 with the mid-tile barrier of waves 0-3 moved from before P5 to before P9 (waves 4-7 unchanged)
# speedup vs baseline: 1.0057x; 1.0057x over previous
; #define ATT_PV(v_, p_) do { const bf16x8 pf_ = __builtin_bit_cast(bf16x8, (p_)); _Pragma("unroll") for (int d = 0; d < 4; ++d) { \
;         const bf16x8 vf_ = __builtin_shufflevector((v_)[2 * d], (v_)[2 * d + 1], 0, 1, 2, 3, 4, 5, 6, 7); O[d] = MFMA32(vf_, pf_, O[d]); } } while (0)
; template <bool ONLINE, int NO>
; __device__ __forceinline__ void softmax_tile(f32x16 (&s)[2], float& m, float& l, f32x16 (&O)[NO], u32x4 (&pk)[4]) {
;     ...
;     float ps = 0.f;
; #pragma unroll
;     for (int blk = 0; blk < 2; ++blk)
; #pragma unroll
;         for (int i = 0; i < 16; ++i) { const float p = __builtin_amdgcn_exp2f(ONLINE ? (s[blk][i] - mn) : s[blk][i]); ps += p; s[blk][i] = p; }
;     l += ps;
; #pragma unroll
;     for (int blk = 0; blk < 2; ++blk)
; #pragma unroll
;         for (int sh = 0; sh < 2; ++sh) { u32x4 pw;
;             pw.x = cvt_pk_bf16(s[blk][8 * sh], s[blk][8 * sh + 1]); pw.y = cvt_pk_bf16(s[blk][8 * sh + 2], s[blk][8 * sh + 3]);
;             pw.z = cvt_pk_bf16(s[blk][8 * sh + 4], s[blk][8 * sh + 5]); pw.w = cvt_pk_bf16(s[blk][8 * sh + 6], s[blk][8 * sh + 7]); pk[2 * blk + sh] = pw; }
; template <int MODE>
; __device__ __forceinline__ void attn_unit(const Params& P, LAS unsigned char* lds, const int b, const int h, const int qb) {
;     ...
;             softmax_tile<ONLINE, 4>(s, m1, l1, O, pk1);
;             if constexpr (MODE == 1) {
;                 v_issue<2>(vc, vaddr); v_wait<15>(va); ATT_PV(va, pk1[0]); v_issue<3>(vd, vaddr); v_wait<15>(vb); ATT_PV(vb, pk1[1]); v_wait<8>(vc); ATT_PV(vc, pk1[2]); v_wait<0>(vd); ATT_PV(vd, pk1[3]);
.Lm1_fast:
	s_cmpk_lt_u32 s58, 0x100
	s_cbranch_scc0 .Lm1_fastB
	v_mfma_f32_32x32x16_bf16 v[96:111], v[2:5], v[112:115], 0
	v_mfma_f32_32x32x16_bf16 v[96:111], v[10:13], v[116:119], v[96:111]
	v_mfma_f32_32x32x16_bf16 v[96:111], v[168:171], v[120:123], v[96:111]
	v_mfma_f32_32x32x16_bf16 v[96:111], v[180:183], v[124:127], v[96:111]
	ds_read_b64_tr_b16 v[168:169], v0 offset:0x1000
	ds_read_b64_tr_b16 v[170:171], v0 offset:0x1100
	ds_read_b64_tr_b16 v[10:11], v0 offset:0x1200
	ds_read_b64_tr_b16 v[12:13], v0 offset:0x1300
	ds_read_b64_tr_b16 v[180:181], v0 offset:0x1400
	ds_read_b64_tr_b16 v[182:183], v0 offset:0x1500
	ds_read_b64_tr_b16 v[2:3], v0 offset:0x1600
	ds_read_b64_tr_b16 v[4:5], v0 offset:0x1700
	v_mfma_f32_32x32x16_bf16 v[80:95], v[6:9], v[112:115], 0
	s_nop 2
	v_exp_f32_e32 v14, v96
	v_exp_f32_e32 v15, v97
	v_mfma_f32_32x32x16_bf16 v[80:95], v[128:131], v[116:119], v[80:95]
	v_exp_f32_e32 v240, v98
	v_exp_f32_e32 v241, v99
	v_exp_f32_e32 v242, v100
	v_mfma_f32_32x32x16_bf16 v[80:95], v[172:175], v[120:123], v[80:95]
	v_exp_f32_e32 v243, v101
	v_exp_f32_e32 v244, v102
	v_exp_f32_e32 v245, v103
	v_mfma_f32_32x32x16_bf16 v[80:95], v[184:187], v[124:127], v[80:95]
	v_cvt_pk_bf16_f32 v96, v14, v15
	v_cvt_pk_bf16_f32 v97, v240, v241
	v_cvt_pk_bf16_f32 v98, v242, v243
	v_cvt_pk_bf16_f32 v99, v244, v245
	v_exp_f32_e32 v246, v104
	s_waitcnt lgkmcnt(8)
	v_mfma_f32_32x32x16_bf16 v[64:79], v[144:147], v[96:99], v[64:79]
	ds_read_b64_tr_b16 v[6:7], v0 offset:0x2000
	ds_read_b64_tr_b16 v[8:9], v0 offset:0x2100
	ds_read_b64_tr_b16 v[128:129], v0 offset:0x2200
	ds_read_b64_tr_b16 v[130:131], v0 offset:0x2300
	ds_read_b64_tr_b16 v[172:173], v0 offset:0x2400
	ds_read_b64_tr_b16 v[174:175], v0 offset:0x2500
	ds_read_b64_tr_b16 v[184:185], v0 offset:0x2600
	ds_read_b64_tr_b16 v[186:187], v0 offset:0x2700
	v_mfma_f32_32x32x16_bf16 v[48:63], v[140:143], v[96:99], v[48:63]
	v_exp_f32_e32 v247, v105
	v_exp_f32_e32 v248, v106
	v_exp_f32_e32 v249, v107
	v_mfma_f32_32x32x16_bf16 v[32:47], v[136:139], v[96:99], v[32:47]
	v_exp_f32_e32 v250, v108
	v_exp_f32_e32 v251, v109
	v_exp_f32_e32 v252, v110
	v_mfma_f32_32x32x16_bf16 v[16:31], v[132:135], v[96:99], v[16:31]
	v_exp_f32_e32 v253, v111
	v_add_f32_e32 v14, v15, v14
	v_cvt_pk_bf16_f32 v100, v246, v247
	v_cvt_pk_bf16_f32 v101, v248, v249
	v_cvt_pk_bf16_f32 v102, v250, v251
	v_add_f32_e32 v14, v240, v14
	v_cvt_pk_bf16_f32 v103, v252, v253
	v_add_f32_e32 v14, v241, v14
	s_waitcnt lgkmcnt(8)
	v_mfma_f32_32x32x16_bf16 v[64:79], v[168:171], v[100:103], v[64:79]
	ds_read_b64_tr_b16 v[144:145], v0 offset:0x3000
	ds_read_b64_tr_b16 v[146:147], v0 offset:0x3100
	ds_read_b64_tr_b16 v[140:141], v0 offset:0x3200
	ds_read_b64_tr_b16 v[142:143], v0 offset:0x3300
	ds_read_b64_tr_b16 v[136:137], v0 offset:0x3400
	ds_read_b64_tr_b16 v[138:139], v0 offset:0x3500
	ds_read_b64_tr_b16 v[132:133], v0 offset:0x3600
	ds_read_b64_tr_b16 v[134:135], v0 offset:0x3700
	v_mfma_f32_32x32x16_bf16 v[48:63], v[10:13], v[100:103], v[48:63]
	v_exp_f32_e32 v104, v80
	v_exp_f32_e32 v105, v81
	v_exp_f32_e32 v106, v82
	v_mfma_f32_32x32x16_bf16 v[32:47], v[180:183], v[100:103], v[32:47]
	v_exp_f32_e32 v107, v83
	v_exp_f32_e32 v108, v84
	v_exp_f32_e32 v109, v85
	v_mfma_f32_32x32x16_bf16 v[16:31], v[2:5], v[100:103], v[16:31]
	v_exp_f32_e32 v110, v86
	v_exp_f32_e32 v111, v87
	v_cvt_pk_bf16_f32 v80, v104, v105
	v_cvt_pk_bf16_f32 v81, v106, v107
	v_cvt_pk_bf16_f32 v82, v108, v109
	v_add_f32_e32 v14, v242, v14
	v_cvt_pk_bf16_f32 v83, v110, v111
	v_add_f32_e32 v14, v243, v14
	s_barrier
	s_waitcnt lgkmcnt(8)
	v_mfma_f32_32x32x16_bf16 v[64:79], v[6:9], v[80:83], v[64:79]
	v_exp_f32_e32 v2, v88
	v_exp_f32_e32 v3, v89
	v_exp_f32_e32 v4, v90
	v_mfma_f32_32x32x16_bf16 v[48:63], v[128:131], v[80:83], v[48:63]
	v_exp_f32_e32 v5, v91
	v_exp_f32_e32 v10, v92
	v_exp_f32_e32 v11, v93
	v_mfma_f32_32x32x16_bf16 v[32:47], v[172:175], v[80:83], v[32:47]
	v_exp_f32_e32 v12, v94
	v_exp_f32_e32 v13, v95
	v_add_f32_e32 v14, v244, v14
	v_add_f32_e32 v14, v245, v14
	v_mfma_f32_32x32x16_bf16 v[16:31], v[184:187], v[80:83], v[16:31]
	v_cvt_pk_bf16_f32 v84, v2, v3
	v_cvt_pk_bf16_f32 v85, v4, v5
	v_cvt_pk_bf16_f32 v86, v10, v11
	v_add_f32_e32 v14, v246, v14
	v_cvt_pk_bf16_f32 v87, v12, v13
	v_add_f32_e32 v14, v247, v14
	v_add_f32_e32 v14, v248, v14
	s_waitcnt lgkmcnt(0)
	v_add_f32_e32 v14, v249, v14
	v_add_f32_e32 v14, v250, v14
	v_add_f32_e32 v14, v251, v14
	v_add_f32_e32 v14, v252, v14
	v_add_f32_e32 v14, v253, v14
	s_add_i32 s41, s40, 3
	s_cmp_ge_u32 s41, s22
	s_cbranch_scc1 .Lm1f_nodma
	s_cmpk_gt_u32 s58, 0xff
	s_cbranch_scc1 .Lm1f_nodma
	v_mfma_f32_32x32x16_bf16 v[64:79], v[144:147], v[84:87], v[64:79]
	s_mov_b64 s[70:71], 0x1000
	s_add_i32 s41, s38, 0x18000
	s_and_b32 s41, s41, 0x18000
	s_add_i32 s41, s77, s41
	v_lshl_add_u64 v[240:241], v[152:153], 0, s[68:69]
	v_lshl_add_u64 v[242:243], v[240:241], 0, s[42:43]
	s_mov_b32 m0, s41
	v_lshl_add_u64 v[240:241], v[240:241], 0, s[44:45]
	global_load_lds_dwordx4 v[242:243], off
	v_mfma_f32_32x32x16_bf16 v[48:63], v[140:143], v[84:87], v[48:63]
	s_add_i32 m0, s41, 0x1000
	v_lshl_add_u64 v[242:243], v[242:243], 0, s[70:71]
	global_load_lds_dwordx4 v[242:243], off
	s_add_i32 m0, s41, 0x2000
	v_lshl_add_u64 v[242:243], v[240:241], 0, s[70:71]
	global_load_lds_dwordx4 v[240:241], off
	s_add_i32 m0, s41, 0x3000
	v_lshl_add_u64 v[240:241], v[154:155], 0, s[68:69]
	global_load_lds_dwordx4 v[242:243], off
	v_add_f32_e32 v14, v104, v14
	v_add_f32_e32 v14, v105, v14
	v_add_f32_e32 v14, v106, v14
	v_add_f32_e32 v14, v107, v14
	v_mfma_f32_32x32x16_bf16 v[32:47], v[136:139], v[84:87], v[32:47]
	v_lshl_add_u64 v[242:243], v[240:241], 0, s[48:49]
	s_add_i32 m0, s41, 0x4000
	v_lshl_add_u64 v[240:241], v[240:241], 0, s[50:51]
	global_load_lds_dwordx4 v[242:243], off
	s_add_i32 m0, s41, 0x5000
	v_lshl_add_u64 v[242:243], v[242:243], 0, s[70:71]
	global_load_lds_dwordx4 v[242:243], off
	v_add_f32_e32 v14, v108, v14
	v_add_f32_e32 v14, v109, v14
	v_add_f32_e32 v14, v110, v14
	v_add_f32_e32 v14, v111, v14
	v_add_f32_e32 v14, v2, v14
	v_add_f32_e32 v14, v3, v14
	v_mfma_f32_32x32x16_bf16 v[16:31], v[132:135], v[84:87], v[16:31]
	s_add_i32 m0, s41, 0x6000
	v_lshl_add_u64 v[242:243], v[240:241], 0, s[70:71]
	global_load_lds_dwordx4 v[240:241], off
	s_add_i32 m0, s41, 0x7000
	s_nop 0
	global_load_lds_dwordx4 v[242:243], off
	v_add_f32_e32 v14, v4, v14
	v_add_f32_e32 v14, v5, v14
	v_add_f32_e32 v14, v10, v14
	v_add_f32_e32 v14, v11, v14
	v_add_f32_e32 v14, v12, v14
	v_add_f32_e32 v14, v13, v14
	v_add_f32_e32 v163, v163, v14
	s_branch .LBB0_474
